# W_out GEMM K-loop: removed the compiler's full vmcnt(0) drain at the top of every iteration (the loop's own counted waits and barriers already order the LDS-DMA ring, as in the other three GEMM loops)
# speedup vs baseline: 1.0018x; 1.0018x over previous
; #define PG8_STAGE(bufoff, gbase, voff) do { _Pragma("unroll") for (int _i = 0; _i < 2; ++_i) \
;         __builtin_amdgcn_global_load_lds((const unsigned*)((const char*)(gbase) + (voff)[_i]), (PG8_LAS unsigned*)(lds + (bufoff) + ldsw + _i * 8192), 16, 0, 0); } while (0)
; #define PG8_LDA(dst, b, h) do { _Pragma("unroll") for (int m = 0; m < 4; ++m) _Pragma("unroll") for (int k = 0; k < 2; ++k) dst[m][k] = *(const PG8_LAS bf16x8*)(lds + PG8_SA(b, h) + aoff + m * 2048 + k * 1024); } while (0)
; #define PG8_LDB(dst, b, h) do { _Pragma("unroll") for (int n = 0; n < 2; ++n) _Pragma("unroll") for (int k = 0; k < 2; ++k) dst[n][k] = *(const PG8_LAS bf16x8*)(lds + PG8_SB(b, h) + boff + n * 2048 + k * 1024); } while (0)
; #define PG8_MMA(ai, bj, At, Bt) do { __builtin_amdgcn_s_setprio(1); _Pragma("unroll") for (int m = 0; m < 4; ++m) _Pragma("unroll") for (int n = 0; n < 2; ++n) _Pragma("unroll") for (int k = 0; k < 2; ++k) \
;         acc[ai][bj][m][n] = __builtin_amdgcn_mfma_f32_16x16x32_bf16(Bt[n][k], At[m][k], acc[ai][bj][m][n], 0, 0, 0); __builtin_amdgcn_s_setprio(0); } while (0)
; #define PG8_WAIT_V(n) asm volatile("s_waitcnt vmcnt(" #n ")" ::: "memory")
; #define PG8_WAIT_L(n) asm volatile("s_waitcnt lgkmcnt(" #n ")" ::: "memory")
; #define PG8_BAR __builtin_amdgcn_s_barrier()
; #define PG8_SCHED __builtin_amdgcn_sched_barrier(0)
; template <class Epi, class Sched, bool ALIGN_EPI = false, bool SP2 = false>
; __device__ __forceinline__ void gemm_phase(PG8_LAS unsigned char* lds, const Gemm g, const Sched& S, const Epi& E, const int tid) {
;     ...
;             PG8_LDB(B0, 0, 0); PG8_LDB(B1, 0, 1); PG8_SCHED; PG8_LDA(At, 0, 0); PG8_STAGE(PG8_SA(1, 1), a1 + hstep, voffA);
;             PG8_WAIT_V(8); PG8_WAIT_L(0); PG8_BAR; PG8_MMA(0, 0, At, B0); PG8_MMA(0, 1, At, B1); PG8_BAR; PG8_SCHED;
;             PG8_LDA(At, 0, 1); PG8_STAGE(PG8_SB(0, 0), b2, voffB); PG8_STAGE(PG8_SB(0, 1), b2 + hstep, voffB); PG8_STAGE(PG8_SA(0, 0), a2, voffA);
;             PG8_WAIT_V(8); PG8_WAIT_L(0); PG8_BAR; PG8_MMA(1, 0, At, B0); PG8_MMA(1, 1, At, B1); PG8_BAR; PG8_SCHED;
.LBB0_126:
	s_add_u32 s36, s88, 0xfffc0080
	s_addc_u32 s37, s89, -1
	s_add_i32 s62, 0, 0x10000
	s_cmp_eq_u32 s61, 12
	s_cselect_b32 s37, s11, s37
	s_cselect_b32 s36, s39, s36
	s_cselect_b32 vcc_hi, s41, s31
	s_cselect_b32 vcc_lo, s60, s30
	s_add_i32 s64, 0, 0x14000
	v_add_u32_e32 v38, s62, v189
	v_add_u32_e32 v70, s64, v189
	ds_read_b128 v[26:29], v38
	ds_read_b128 v[30:33], v38 offset:1024
	ds_read_b128 v[34:37], v38 offset:2048
	ds_read_b128 v[38:41], v38 offset:3072
	ds_read_b128 v[58:61], v70
	ds_read_b128 v[62:65], v70 offset:1024
	ds_read_b128 v[66:69], v70 offset:2048
	ds_read_b128 v[70:73], v70 offset:3072
	v_lshl_add_u64 v[180:181], s[88:89], 0, v[168:169]
	s_add_i32 m0, s2, 0xc000
	ds_read_b128 v[172:175], v196
	ds_read_b128 v[176:179], v196 offset:1024
	ds_read_b128 v[198:201], v196 offset:2048
	ds_read_b128 v[202:205], v196 offset:3072
	ds_read_b128 v[206:209], v196 offset:4096
	ds_read_b128 v[210:213], v196 offset:5120
	ds_read_b128 v[214:217], v196 offset:6144
	ds_read_b128 v[234:237], v196 offset:7168
	global_load_lds_dwordx4 v[180:181], off
	v_lshl_add_u64 v[180:181], s[88:89], 0, v[170:171]
	s_add_i32 m0, s2, 0xe000
	s_nop 0
	global_load_lds_dwordx4 v[180:181], off
	s_waitcnt vmcnt(8)
	s_waitcnt lgkmcnt(0)
	s_barrier
	s_setprio 1
	s_waitcnt lgkmcnt(0)
	v_mfma_f32_16x16x32_bf16 v[158:161], v[26:29], v[172:175], v[158:161]
	v_mfma_f32_16x16x32_bf16 v[154:157], v[34:37], v[172:175], v[154:157]
	v_mfma_f32_16x16x32_bf16 v[142:145], v[26:29], v[198:201], v[142:145]
	v_mfma_f32_16x16x32_bf16 v[138:141], v[34:37], v[198:201], v[138:141]
	v_mfma_f32_16x16x32_bf16 v[126:129], v[26:29], v[206:209], v[126:129]
	v_mfma_f32_16x16x32_bf16 v[122:125], v[34:37], v[206:209], v[122:125]
	v_mfma_f32_16x16x32_bf16 v[110:113], v[26:29], v[214:217], v[110:113]
	v_mfma_f32_16x16x32_bf16 v[106:109], v[34:37], v[214:217], v[106:109]
	v_mfma_f32_16x16x32_bf16 v[158:161], v[30:33], v[176:179], v[158:161]
	v_mfma_f32_16x16x32_bf16 v[154:157], v[38:41], v[176:179], v[154:157]
	v_mfma_f32_16x16x32_bf16 v[142:145], v[30:33], v[202:205], v[142:145]
	v_mfma_f32_16x16x32_bf16 v[138:141], v[38:41], v[202:205], v[138:141]
	v_mfma_f32_16x16x32_bf16 v[126:129], v[30:33], v[210:213], v[126:129]
	v_mfma_f32_16x16x32_bf16 v[122:125], v[38:41], v[210:213], v[122:125]
	v_mfma_f32_16x16x32_bf16 v[110:113], v[30:33], v[234:237], v[110:113]
	v_mfma_f32_16x16x32_bf16 v[106:109], v[38:41], v[234:237], v[106:109]
	s_setprio 0
	s_setprio 1
	v_mfma_f32_16x16x32_bf16 v[150:153], v[58:61], v[172:175], v[150:153]
	v_mfma_f32_16x16x32_bf16 v[146:149], v[66:69], v[172:175], v[146:149]
	v_mfma_f32_16x16x32_bf16 v[134:137], v[58:61], v[198:201], v[134:137]
	v_mfma_f32_16x16x32_bf16 v[130:133], v[66:69], v[198:201], v[130:133]
	v_mfma_f32_16x16x32_bf16 v[118:121], v[58:61], v[206:209], v[118:121]
	v_mfma_f32_16x16x32_bf16 v[114:117], v[66:69], v[206:209], v[114:117]
	v_mfma_f32_16x16x32_bf16 v[102:105], v[58:61], v[214:217], v[102:105]
	v_mfma_f32_16x16x32_bf16 v[98:101], v[66:69], v[214:217], v[98:101]
	v_mfma_f32_16x16x32_bf16 v[150:153], v[62:65], v[176:179], v[150:153]
	v_mfma_f32_16x16x32_bf16 v[146:149], v[70:73], v[176:179], v[146:149]
	v_mfma_f32_16x16x32_bf16 v[134:137], v[62:65], v[202:205], v[134:137]
	v_mfma_f32_16x16x32_bf16 v[130:133], v[70:73], v[202:205], v[130:133]
	v_mfma_f32_16x16x32_bf16 v[118:121], v[62:65], v[210:213], v[118:121]
	v_mfma_f32_16x16x32_bf16 v[114:117], v[70:73], v[210:213], v[114:117]
	v_mfma_f32_16x16x32_bf16 v[102:105], v[62:65], v[234:237], v[102:105]
	v_mfma_f32_16x16x32_bf16 v[98:101], v[70:73], v[234:237], v[98:101]
	s_setprio 0
	s_barrier
	s_add_i32 s62, s62, s20
	v_lshl_add_u64 v[180:181], vcc, 0, v[0:1]
	s_mov_b32 m0, s62
	ds_read_b128 v[172:175], v196 offset:16384
	ds_read_b128 v[176:179], v196 offset:17408
	ds_read_b128 v[198:201], v196 offset:18432
	ds_read_b128 v[202:205], v196 offset:19456
	ds_read_b128 v[206:209], v196 offset:20480
	ds_read_b128 v[210:213], v196 offset:21504
	ds_read_b128 v[214:217], v196 offset:22528
	ds_read_b128 v[234:237], v196 offset:23552
	global_load_lds_dwordx4 v[180:181], off
	s_add_i32 m0, s62, 0x2000
	s_add_u32 s62, vcc_lo, 0x40000
	v_lshl_add_u64 v[190:191], vcc, 0, v[162:163]
	s_addc_u32 s63, vcc_hi, 0
	s_add_i32 s64, s64, s20
	global_load_lds_dwordx4 v[190:191], off
	v_lshl_add_u64 v[238:239], s[62:63], 0, v[0:1]
	s_mov_b32 m0, s64
	v_lshl_add_u64 v[242:243], s[36:37], 0, v[166:167]
	global_load_lds_dwordx4 v[238:239], off
	v_lshl_add_u64 v[238:239], s[62:63], 0, v[162:163]
	s_add_i32 m0, s64, 0x2000
	v_lshl_add_u64 v[244:245], s[36:37], 0, v[164:165]
	global_load_lds_dwordx4 v[238:239], off
	s_mov_b32 m0, s2
	s_nop 0
	global_load_lds_dwordx4 v[242:243], off
	s_mov_b32 m0, s3
	s_nop 0
	global_load_lds_dwordx4 v[244:245], off
	s_waitcnt vmcnt(8)
	s_waitcnt lgkmcnt(0)
	s_barrier
; #define PG8_STAGE(bufoff, gbase, voff) do { _Pragma("unroll") for (int _i = 0; _i < 2; ++_i) \
;         __builtin_amdgcn_global_load_lds((const unsigned*)((const char*)(gbase) + (voff)[_i]), (PG8_LAS unsigned*)(lds + (bufoff) + ldsw + _i * 8192), 16, 0, 0); } while (0)
; #define PG8_LDA(dst, b, h) do { _Pragma("unroll") for (int m = 0; m < 4; ++m) _Pragma("unroll") for (int k = 0; k < 2; ++k) dst[m][k] = *(const PG8_LAS bf16x8*)(lds + PG8_SA(b, h) + aoff + m * 2048 + k * 1024); } while (0)
; #define PG8_LDB(dst, b, h) do { _Pragma("unroll") for (int n = 0; n < 2; ++n) _Pragma("unroll") for (int k = 0; k < 2; ++k) dst[n][k] = *(const PG8_LAS bf16x8*)(lds + PG8_SB(b, h) + boff + n * 2048 + k * 1024); } while (0)
; #define PG8_MMA(ai, bj, At, Bt) do { __builtin_amdgcn_s_setprio(1); _Pragma("unroll") for (int m = 0; m < 4; ++m) _Pragma("unroll") for (int n = 0; n < 2; ++n) _Pragma("unroll") for (int k = 0; k < 2; ++k) \
;         acc[ai][bj][m][n] = __builtin_amdgcn_mfma_f32_16x16x32_bf16(Bt[n][k], At[m][k], acc[ai][bj][m][n], 0, 0, 0); __builtin_amdgcn_s_setprio(0); } while (0)
; #define PG8_WAIT_V(n) asm volatile("s_waitcnt vmcnt(" #n ")" ::: "memory")
; #define PG8_WAIT_L(n) asm volatile("s_waitcnt lgkmcnt(" #n ")" ::: "memory")
; #define PG8_BAR __builtin_amdgcn_s_barrier()
; #define PG8_SCHED __builtin_amdgcn_sched_barrier(0)
; template <class Epi, class Sched, bool ALIGN_EPI = false, bool SP2 = false>
; __device__ __forceinline__ void gemm_phase(PG8_LAS unsigned char* lds, const Gemm g, const Sched& S, const Epi& E, const int tid) {
;     ...
;             PG8_WAIT_V(8); PG8_WAIT_L(0); PG8_BAR; PG8_MMA(1, 0, At, B0); PG8_MMA(1, 1, At, B1); PG8_BAR; PG8_SCHED;
;             PG8_LDB(B0, 1, 0); PG8_LDB(B1, 1, 1); PG8_SCHED; PG8_LDA(At, 1, 0); PG8_STAGE(PG8_SA(0, 1), a2 + hstep, voffA);
;             PG8_WAIT_V(8); PG8_WAIT_L(0); PG8_BAR; PG8_MMA(0, 0, At, B0); PG8_MMA(0, 1, At, B1); PG8_BAR; PG8_SCHED;
	s_setprio 1
	s_waitcnt lgkmcnt(0)
	v_mfma_f32_16x16x32_bf16 v[94:97], v[26:29], v[172:175], v[94:97]
	v_mfma_f32_16x16x32_bf16 v[90:93], v[34:37], v[172:175], v[90:93]
	v_mfma_f32_16x16x32_bf16 v[78:81], v[26:29], v[198:201], v[78:81]
	v_mfma_f32_16x16x32_bf16 v[74:77], v[34:37], v[198:201], v[74:77]
	v_mfma_f32_16x16x32_bf16 v[46:49], v[26:29], v[206:209], v[46:49]
	v_mfma_f32_16x16x32_bf16 v[42:45], v[34:37], v[206:209], v[42:45]
	v_mfma_f32_16x16x32_bf16 v[14:17], v[26:29], v[214:217], v[14:17]
	v_mfma_f32_16x16x32_bf16 v[10:13], v[34:37], v[214:217], v[10:13]
	v_mfma_f32_16x16x32_bf16 v[94:97], v[30:33], v[176:179], v[94:97]
	v_mfma_f32_16x16x32_bf16 v[90:93], v[38:41], v[176:179], v[90:93]
	v_mfma_f32_16x16x32_bf16 v[78:81], v[30:33], v[202:205], v[78:81]
	v_mfma_f32_16x16x32_bf16 v[74:77], v[38:41], v[202:205], v[74:77]
	v_mfma_f32_16x16x32_bf16 v[46:49], v[30:33], v[210:213], v[46:49]
	v_mfma_f32_16x16x32_bf16 v[42:45], v[38:41], v[210:213], v[42:45]
	v_mfma_f32_16x16x32_bf16 v[14:17], v[30:33], v[234:237], v[14:17]
	v_mfma_f32_16x16x32_bf16 v[10:13], v[38:41], v[234:237], v[10:13]
	s_setprio 0
	s_setprio 1
	v_mfma_f32_16x16x32_bf16 v[22:25], v[58:61], v[206:209], v[22:25]
	v_mfma_f32_16x16x32_bf16 v[18:21], v[66:69], v[206:209], v[18:21]
	v_mfma_f32_16x16x32_bf16 v[6:9], v[58:61], v[214:217], v[6:9]
	v_mfma_f32_16x16x32_bf16 v[2:5], v[66:69], v[214:217], v[2:5]
	v_mfma_f32_16x16x32_bf16 v[26:29], v[58:61], v[172:175], v[86:89]
	v_mfma_f32_16x16x32_bf16 v[30:33], v[66:69], v[172:175], v[82:85]
	v_mfma_f32_16x16x32_bf16 v[34:37], v[58:61], v[198:201], v[54:57]
	v_mfma_f32_16x16x32_bf16 v[38:41], v[66:69], v[198:201], v[50:53]
	v_mfma_f32_16x16x32_bf16 v[22:25], v[62:65], v[210:213], v[22:25]
	v_mfma_f32_16x16x32_bf16 v[18:21], v[70:73], v[210:213], v[18:21]
	v_mfma_f32_16x16x32_bf16 v[6:9], v[62:65], v[234:237], v[6:9]
	v_mfma_f32_16x16x32_bf16 v[2:5], v[70:73], v[234:237], v[2:5]
	v_mfma_f32_16x16x32_bf16 v[26:29], v[62:65], v[176:179], v[26:29]
	v_mfma_f32_16x16x32_bf16 v[30:33], v[70:73], v[176:179], v[30:33]
	v_mfma_f32_16x16x32_bf16 v[34:37], v[62:65], v[202:205], v[34:37]
	v_mfma_f32_16x16x32_bf16 v[38:41], v[70:73], v[202:205], v[38:41]
	s_setprio 0
	s_barrier
	s_add_i32 s62, 0, 0x18000
	s_add_i32 s63, 0, 0x1c000
	v_add_u32_e32 v62, s62, v189
	v_add_u32_e32 v82, s63, v189
	ds_read_b128 v[50:53], v62
	ds_read_b128 v[54:57], v62 offset:1024
	ds_read_b128 v[58:61], v62 offset:2048
	ds_read_b128 v[62:65], v62 offset:3072
	ds_read_b128 v[66:69], v82
	ds_read_b128 v[70:73], v82 offset:1024
	ds_read_b128 v[172:175], v82 offset:2048
	ds_read_b128 v[176:179], v82 offset:3072
	s_add_u32 s36, s36, 0x40000
	s_addc_u32 s37, s37, 0
	s_mov_b32 m0, s6
	v_lshl_add_u64 v[238:239], s[36:37], 0, v[166:167]
	ds_read_b128 v[82:85], v196 offset:32768
	ds_read_b128 v[86:89], v196 offset:33792
	ds_read_b128 v[198:201], v196 offset:34816
	ds_read_b128 v[202:205], v196 offset:35840
	ds_read_b128 v[206:209], v196 offset:36864
	ds_read_b128 v[210:213], v196 offset:37888
	ds_read_b128 v[214:217], v196 offset:38912
	ds_read_b128 v[234:237], v196 offset:39936
	global_load_lds_dwordx4 v[238:239], off
	v_lshl_add_u64 v[238:239], s[36:37], 0, v[164:165]
	s_mov_b32 m0, s7
	s_nop 0
	global_load_lds_dwordx4 v[238:239], off
	s_waitcnt vmcnt(8)
	s_waitcnt lgkmcnt(0)
	s_barrier
	s_setprio 1
	s_waitcnt lgkmcnt(0)
	v_mfma_f32_16x16x32_bf16 v[158:161], v[50:53], v[82:85], v[158:161]
	v_mfma_f32_16x16x32_bf16 v[154:157], v[58:61], v[82:85], v[154:157]
	v_mfma_f32_16x16x32_bf16 v[142:145], v[50:53], v[198:201], v[142:145]
	v_mfma_f32_16x16x32_bf16 v[138:141], v[58:61], v[198:201], v[138:141]
	v_mfma_f32_16x16x32_bf16 v[126:129], v[50:53], v[206:209], v[126:129]
	v_mfma_f32_16x16x32_bf16 v[122:125], v[58:61], v[206:209], v[122:125]
	v_mfma_f32_16x16x32_bf16 v[110:113], v[50:53], v[214:217], v[110:113]
	v_mfma_f32_16x16x32_bf16 v[106:109], v[58:61], v[214:217], v[106:109]
	v_mfma_f32_16x16x32_bf16 v[158:161], v[54:57], v[86:89], v[158:161]
	v_mfma_f32_16x16x32_bf16 v[154:157], v[62:65], v[86:89], v[154:157]
	v_mfma_f32_16x16x32_bf16 v[142:145], v[54:57], v[202:205], v[142:145]
	v_mfma_f32_16x16x32_bf16 v[138:141], v[62:65], v[202:205], v[138:141]
	v_mfma_f32_16x16x32_bf16 v[126:129], v[54:57], v[210:213], v[126:129]
	v_mfma_f32_16x16x32_bf16 v[122:125], v[62:65], v[210:213], v[122:125]
	v_mfma_f32_16x16x32_bf16 v[110:113], v[54:57], v[234:237], v[110:113]
	v_mfma_f32_16x16x32_bf16 v[106:109], v[62:65], v[234:237], v[106:109]
	s_setprio 0
	s_setprio 1
	v_mfma_f32_16x16x32_bf16 v[150:153], v[66:69], v[82:85], v[150:153]
	v_mfma_f32_16x16x32_bf16 v[82:85], v[172:175], v[82:85], v[146:149]
	v_mfma_f32_16x16x32_bf16 v[146:149], v[176:179], v[86:89], v[82:85]
	v_mfma_f32_16x16x32_bf16 v[82:85], v[66:69], v[198:201], v[134:137]
	v_mfma_f32_16x16x32_bf16 v[134:137], v[70:73], v[202:205], v[82:85]
	v_mfma_f32_16x16x32_bf16 v[82:85], v[172:175], v[198:201], v[130:133]
	v_mfma_f32_16x16x32_bf16 v[130:133], v[176:179], v[202:205], v[82:85]
	v_mfma_f32_16x16x32_bf16 v[82:85], v[66:69], v[206:209], v[118:121]
	v_mfma_f32_16x16x32_bf16 v[118:121], v[70:73], v[210:213], v[82:85]
	v_mfma_f32_16x16x32_bf16 v[82:85], v[172:175], v[206:209], v[114:117]
	v_mfma_f32_16x16x32_bf16 v[114:117], v[176:179], v[210:213], v[82:85]
	v_mfma_f32_16x16x32_bf16 v[82:85], v[66:69], v[214:217], v[102:105]
	v_mfma_f32_16x16x32_bf16 v[102:105], v[70:73], v[234:237], v[82:85]
	v_mfma_f32_16x16x32_bf16 v[82:85], v[172:175], v[214:217], v[98:101]
	v_mfma_f32_16x16x32_bf16 v[150:153], v[70:73], v[86:89], v[150:153]
	v_mfma_f32_16x16x32_bf16 v[98:101], v[176:179], v[234:237], v[82:85]
	s_setprio 0
	s_barrier
; #define PG8_STAGE(bufoff, gbase, voff) do { _Pragma("unroll") for (int _i = 0; _i < 2; ++_i) \
;         __builtin_amdgcn_global_load_lds((const unsigned*)((const char*)(gbase) + (voff)[_i]), (PG8_LAS unsigned*)(lds + (bufoff) + ldsw + _i * 8192), 16, 0, 0); } while (0)
; #define PG8_LDA(dst, b, h) do { _Pragma("unroll") for (int m = 0; m < 4; ++m) _Pragma("unroll") for (int k = 0; k < 2; ++k) dst[m][k] = *(const PG8_LAS bf16x8*)(lds + PG8_SA(b, h) + aoff + m * 2048 + k * 1024); } while (0)
; #define PG8_MMA(ai, bj, At, Bt) do { __builtin_amdgcn_s_setprio(1); _Pragma("unroll") for (int m = 0; m < 4; ++m) _Pragma("unroll") for (int n = 0; n < 2; ++n) _Pragma("unroll") for (int k = 0; k < 2; ++k) \
;         acc[ai][bj][m][n] = __builtin_amdgcn_mfma_f32_16x16x32_bf16(Bt[n][k], At[m][k], acc[ai][bj][m][n], 0, 0, 0); __builtin_amdgcn_s_setprio(0); } while (0)
; #define PG8_WAIT_V(n) asm volatile("s_waitcnt vmcnt(" #n ")" ::: "memory")
; #define PG8_WAIT_L(n) asm volatile("s_waitcnt lgkmcnt(" #n ")" ::: "memory")
; #define PG8_BAR __builtin_amdgcn_s_barrier()
; #define PG8_SCHED __builtin_amdgcn_sched_barrier(0)
; template <class Epi, class Sched, bool ALIGN_EPI = false, bool SP2 = false>
; __device__ __forceinline__ void gemm_phase(PG8_LAS unsigned char* lds, const Gemm g, const Sched& S, const Epi& E, const int tid) {
;     ...
;             PG8_LDA(At, 1, 1); PG8_STAGE(PG8_SB(1, 0), b3, voffB); PG8_STAGE(PG8_SB(1, 1), b3 + hstep, voffB); PG8_STAGE(PG8_SA(1, 0), a3, voffA);
;             PG8_WAIT_V(8); PG8_WAIT_L(0); PG8_BAR; PG8_MMA(1, 0, At, B0); PG8_MMA(1, 1, At, B1); PG8_BAR; PG8_SCHED;
;     ...
;         if constexpr (ALIGN_EPI) { if (wr == 0) PG8_BAR; }
	s_add_i32 s36, s62, s20
	v_lshl_add_u64 v[86:87], v[180:181], 0, s[24:25]
	s_mov_b32 m0, s36
	s_nop 0
	ds_read_b128 v[82:85], v196 offset:49152
	ds_read_b128 v[198:201], v196 offset:50176
	ds_read_b128 v[202:205], v196 offset:51200
	ds_read_b128 v[206:209], v196 offset:52224
	ds_read_b128 v[210:213], v196 offset:53248
	ds_read_b128 v[214:217], v196 offset:54272
	ds_read_b128 v[234:237], v196 offset:55296
	ds_read_b128 v[238:241], v196 offset:56320
	global_load_lds_dwordx4 v[86:87], off
	s_add_i32 m0, s36, 0x2000
	s_add_u32 s36, vcc_lo, 0x40080
	v_lshl_add_u64 v[86:87], v[190:191], 0, s[24:25]
	s_addc_u32 s37, vcc_hi, 0
	s_add_i32 s62, s63, s20
	global_load_lds_dwordx4 v[86:87], off
	v_lshl_add_u64 v[86:87], s[36:37], 0, v[0:1]
	s_mov_b32 m0, s62
	s_nop 0
	global_load_lds_dwordx4 v[86:87], off
	v_lshl_add_u64 v[86:87], s[36:37], 0, v[162:163]
	s_add_i32 m0, s62, 0x2000
	s_nop 0
	global_load_lds_dwordx4 v[86:87], off
	v_lshl_add_u64 v[86:87], v[242:243], 0, s[24:25]
	s_mov_b32 m0, s83
	s_nop 0
	global_load_lds_dwordx4 v[86:87], off
	v_lshl_add_u64 v[86:87], v[244:245], 0, s[24:25]
	s_mov_b32 m0, s96
	s_nop 0
	global_load_lds_dwordx4 v[86:87], off
	s_waitcnt vmcnt(8)
	s_waitcnt lgkmcnt(0)
	s_barrier
	s_setprio 1
	s_waitcnt lgkmcnt(0)
	v_mfma_f32_16x16x32_bf16 v[86:89], v[50:53], v[82:85], v[94:97]
	v_mfma_f32_16x16x32_bf16 v[94:97], v[54:57], v[198:201], v[86:89]
	v_mfma_f32_16x16x32_bf16 v[86:89], v[58:61], v[82:85], v[90:93]
	v_mfma_f32_16x16x32_bf16 v[78:81], v[50:53], v[202:205], v[78:81]
	v_mfma_f32_16x16x32_bf16 v[74:77], v[58:61], v[202:205], v[74:77]
	v_mfma_f32_16x16x32_bf16 v[46:49], v[50:53], v[210:213], v[46:49]
	v_mfma_f32_16x16x32_bf16 v[42:45], v[58:61], v[210:213], v[42:45]
	v_mfma_f32_16x16x32_bf16 v[14:17], v[50:53], v[234:237], v[14:17]
	v_mfma_f32_16x16x32_bf16 v[10:13], v[58:61], v[234:237], v[10:13]
	v_mfma_f32_16x16x32_bf16 v[90:93], v[62:65], v[198:201], v[86:89]
	v_mfma_f32_16x16x32_bf16 v[78:81], v[54:57], v[206:209], v[78:81]
	v_mfma_f32_16x16x32_bf16 v[74:77], v[62:65], v[206:209], v[74:77]
	v_mfma_f32_16x16x32_bf16 v[46:49], v[54:57], v[214:217], v[46:49]
	v_mfma_f32_16x16x32_bf16 v[42:45], v[62:65], v[214:217], v[42:45]
	v_mfma_f32_16x16x32_bf16 v[14:17], v[54:57], v[238:241], v[14:17]
	v_mfma_f32_16x16x32_bf16 v[10:13], v[62:65], v[238:241], v[10:13]
	s_setprio 0
	s_setprio 1
	v_mfma_f32_16x16x32_bf16 v[26:29], v[66:69], v[82:85], v[26:29]
	v_mfma_f32_16x16x32_bf16 v[86:89], v[70:73], v[198:201], v[26:29]
	v_mfma_f32_16x16x32_bf16 v[26:29], v[172:175], v[82:85], v[30:33]
	v_mfma_f32_16x16x32_bf16 v[82:85], v[176:179], v[198:201], v[26:29]
	v_mfma_f32_16x16x32_bf16 v[26:29], v[66:69], v[202:205], v[34:37]
	v_mfma_f32_16x16x32_bf16 v[54:57], v[70:73], v[206:209], v[26:29]
	v_mfma_f32_16x16x32_bf16 v[26:29], v[172:175], v[202:205], v[38:41]
	v_mfma_f32_16x16x32_bf16 v[22:25], v[66:69], v[210:213], v[22:25]
	v_mfma_f32_16x16x32_bf16 v[18:21], v[172:175], v[210:213], v[18:21]
	v_mfma_f32_16x16x32_bf16 v[6:9], v[66:69], v[234:237], v[6:9]
	v_mfma_f32_16x16x32_bf16 v[2:5], v[172:175], v[234:237], v[2:5]
	v_mfma_f32_16x16x32_bf16 v[50:53], v[176:179], v[206:209], v[26:29]
	v_mfma_f32_16x16x32_bf16 v[22:25], v[70:73], v[214:217], v[22:25]
	v_mfma_f32_16x16x32_bf16 v[18:21], v[176:179], v[214:217], v[18:21]
	v_mfma_f32_16x16x32_bf16 v[6:9], v[70:73], v[238:241], v[6:9]
	v_mfma_f32_16x16x32_bf16 v[2:5], v[176:179], v[238:241], v[2:5]
	s_setprio 0
	s_barrier
	s_add_i32 s61, s61, 2
	s_add_u32 s88, s88, 0x100
	s_addc_u32 s89, s89, 0
	s_add_u32 s30, s30, 0x100
	s_addc_u32 s31, s31, 0
	s_cmp_gt_u32 s61, 13
	s_cbranch_scc0 .LBB0_126
	v_readlane_b32 s30, v253, 38
	v_readlane_b32 s31, v253, 39
	s_and_b64 vcc, exec, s[30:31]
	s_cbranch_vccz .LBB0_129
	s_barrier
